# v74 + FFN-in SwiGLU epilogue rewritten: eight sigmoid evaluations in flight instead of a serial chain through one temp, packed f32 scale and +1
# baseline (speedup 1.0000x reference)
.LBB0_178:
	v_lshl_add_u32 v141, s8, 8, v138
	s_lshl_b32 s8, s9, 7
	s_or_b32 s46, s8, s64
	s_ashr_i32 s47, s46, 31
	s_movk_i32 s20, 0x1600
	s_lshl_b64 s[46:47], s[46:47], 1
	s_andn2_b64 vcc, exec, s[44:45]
	v_mov_b64_e32 v[246:247], s[6:7]
	v_mov_b32_e32 v0, 0xbfb8aa3b
	v_mov_b32_e32 v1, 0xbfb8aa3b
	v_mov_b32_e32 v142, 1.0
	v_mov_b32_e32 v143, 1.0
	v_pk_mul_f32 v[232:233], v[124:125], v[0:1]
	v_pk_mul_f32 v[234:235], v[126:127], v[0:1]
	v_pk_mul_f32 v[236:237], v[120:121], v[0:1]
	v_pk_mul_f32 v[238:239], v[122:123], v[0:1]
	v_exp_f32_e32 v232, v232
	v_exp_f32_e32 v233, v233
	v_exp_f32_e32 v234, v234
	v_exp_f32_e32 v235, v235
	v_exp_f32_e32 v236, v236
	v_exp_f32_e32 v237, v237
	v_exp_f32_e32 v238, v238
	v_exp_f32_e32 v239, v239
	v_pk_add_f32 v[232:233], v[232:233], v[142:143]
	v_pk_add_f32 v[234:235], v[234:235], v[142:143]
	v_pk_add_f32 v[236:237], v[236:237], v[142:143]
	v_pk_add_f32 v[238:239], v[238:239], v[142:143]
	v_rcp_f32_e32 v232, v232
	v_rcp_f32_e32 v233, v233
	v_rcp_f32_e32 v234, v234
	v_rcp_f32_e32 v235, v235
	v_rcp_f32_e32 v236, v236
	v_rcp_f32_e32 v237, v237
	v_rcp_f32_e32 v238, v238
	v_rcp_f32_e32 v239, v239
	v_pk_mul_f32 v[124:125], v[124:125], v[232:233]
	v_pk_mul_f32 v[126:127], v[126:127], v[234:235]
	v_pk_mul_f32 v[120:121], v[120:121], v[236:237]
	v_pk_mul_f32 v[122:123], v[122:123], v[238:239]
	v_pk_mul_f32 v[124:125], v[128:129], v[124:125]
	v_pk_mul_f32 v[126:127], v[130:131], v[126:127]
	v_pk_mul_f32 v[120:121], v[116:117], v[120:121]
	v_pk_mul_f32 v[122:123], v[118:119], v[122:123]
	v_cvt_pk_bf16_f32 v240, v124, v125
	v_cvt_pk_bf16_f32 v241, v126, v127
	v_cvt_pk_bf16_f32 v242, v120, v121
	v_cvt_pk_bf16_f32 v243, v122, v123
	v_mad_i64_i32 v[244:245], s[8:9], v141, s20, v[246:247]
	v_lshl_add_u64 v[244:245], v[244:245], 0, s[46:47]
	v_lshl_add_u64 v[244:245], v[244:245], 0, v[2:3]
	v_permlane16_swap_b32_e32 v240, v242
	v_permlane16_swap_b32_e32 v241, v243
	global_store_dwordx4 v[244:245], v[240:243], off
	v_pk_mul_f32 v[232:233], v[112:113], v[0:1]
	v_pk_mul_f32 v[234:235], v[114:115], v[0:1]
	v_pk_mul_f32 v[236:237], v[104:105], v[0:1]
	v_pk_mul_f32 v[238:239], v[106:107], v[0:1]
	v_exp_f32_e32 v232, v232
	v_exp_f32_e32 v233, v233
	v_exp_f32_e32 v234, v234
	v_exp_f32_e32 v235, v235
	v_exp_f32_e32 v236, v236
	v_exp_f32_e32 v237, v237
	v_exp_f32_e32 v238, v238
	v_exp_f32_e32 v239, v239
	v_pk_add_f32 v[232:233], v[232:233], v[142:143]
	v_pk_add_f32 v[234:235], v[234:235], v[142:143]
	v_pk_add_f32 v[236:237], v[236:237], v[142:143]
	v_pk_add_f32 v[238:239], v[238:239], v[142:143]
	v_rcp_f32_e32 v232, v232
	v_rcp_f32_e32 v233, v233
	v_rcp_f32_e32 v234, v234
	v_rcp_f32_e32 v235, v235
	v_rcp_f32_e32 v236, v236
	v_rcp_f32_e32 v237, v237
	v_rcp_f32_e32 v238, v238
	v_rcp_f32_e32 v239, v239
	v_pk_mul_f32 v[112:113], v[112:113], v[232:233]
	v_pk_mul_f32 v[114:115], v[114:115], v[234:235]
	v_pk_mul_f32 v[104:105], v[104:105], v[236:237]
	v_pk_mul_f32 v[106:107], v[106:107], v[238:239]
	v_pk_mul_f32 v[112:113], v[108:109], v[112:113]
	v_pk_mul_f32 v[114:115], v[110:111], v[114:115]
	v_pk_mul_f32 v[104:105], v[100:101], v[104:105]
	v_pk_mul_f32 v[106:107], v[102:103], v[106:107]
	v_cvt_pk_bf16_f32 v248, v112, v113
	v_cvt_pk_bf16_f32 v249, v114, v115
	v_cvt_pk_bf16_f32 v250, v104, v105
	v_cvt_pk_bf16_f32 v251, v106, v107
	v_or_b32_e32 v232, 16, v141
	v_mad_i64_i32 v[252:253], s[8:9], v232, s20, v[246:247]
	v_lshl_add_u64 v[252:253], v[252:253], 0, s[46:47]
	v_lshl_add_u64 v[252:253], v[252:253], 0, v[2:3]
	v_permlane16_swap_b32_e32 v248, v250
	v_permlane16_swap_b32_e32 v249, v251
	global_store_dwordx4 v[252:253], v[248:251], off
	v_pk_mul_f32 v[232:233], v[96:97], v[0:1]
	v_pk_mul_f32 v[234:235], v[98:99], v[0:1]
	v_pk_mul_f32 v[236:237], v[88:89], v[0:1]
	v_pk_mul_f32 v[238:239], v[90:91], v[0:1]
	v_exp_f32_e32 v232, v232
	v_exp_f32_e32 v233, v233
	v_exp_f32_e32 v234, v234
	v_exp_f32_e32 v235, v235
	v_exp_f32_e32 v236, v236
	v_exp_f32_e32 v237, v237
	v_exp_f32_e32 v238, v238
	v_exp_f32_e32 v239, v239
	v_pk_add_f32 v[232:233], v[232:233], v[142:143]
	v_pk_add_f32 v[234:235], v[234:235], v[142:143]
	v_pk_add_f32 v[236:237], v[236:237], v[142:143]
	v_pk_add_f32 v[238:239], v[238:239], v[142:143]
	v_rcp_f32_e32 v232, v232
	v_rcp_f32_e32 v233, v233
	v_rcp_f32_e32 v234, v234
	v_rcp_f32_e32 v235, v235
	v_rcp_f32_e32 v236, v236
	v_rcp_f32_e32 v237, v237
	v_rcp_f32_e32 v238, v238
	v_rcp_f32_e32 v239, v239
	v_pk_mul_f32 v[96:97], v[96:97], v[232:233]
	v_pk_mul_f32 v[98:99], v[98:99], v[234:235]
	v_pk_mul_f32 v[88:89], v[88:89], v[236:237]
	v_pk_mul_f32 v[90:91], v[90:91], v[238:239]
	v_pk_mul_f32 v[96:97], v[92:93], v[96:97]
	v_pk_mul_f32 v[98:99], v[94:95], v[98:99]
	v_pk_mul_f32 v[88:89], v[84:85], v[88:89]
	v_pk_mul_f32 v[90:91], v[86:87], v[90:91]
	v_cvt_pk_bf16_f32 v240, v96, v97
	v_cvt_pk_bf16_f32 v241, v98, v99
	v_cvt_pk_bf16_f32 v242, v88, v89
	v_cvt_pk_bf16_f32 v243, v90, v91
	v_or_b32_e32 v232, 32, v141
	v_mad_i64_i32 v[244:245], s[8:9], v232, s20, v[246:247]
	v_lshl_add_u64 v[244:245], v[244:245], 0, s[46:47]
	v_lshl_add_u64 v[244:245], v[244:245], 0, v[2:3]
	v_permlane16_swap_b32_e32 v240, v242
	v_permlane16_swap_b32_e32 v241, v243
	global_store_dwordx4 v[244:245], v[240:243], off
	v_pk_mul_f32 v[232:233], v[80:81], v[0:1]
	v_pk_mul_f32 v[234:235], v[82:83], v[0:1]
	v_pk_mul_f32 v[236:237], v[72:73], v[0:1]
	v_pk_mul_f32 v[238:239], v[74:75], v[0:1]
	v_exp_f32_e32 v232, v232
	v_exp_f32_e32 v233, v233
	v_exp_f32_e32 v234, v234
	v_exp_f32_e32 v235, v235
	v_exp_f32_e32 v236, v236
	v_exp_f32_e32 v237, v237
	v_exp_f32_e32 v238, v238
	v_exp_f32_e32 v239, v239
	v_pk_add_f32 v[232:233], v[232:233], v[142:143]
	v_pk_add_f32 v[234:235], v[234:235], v[142:143]
	v_pk_add_f32 v[236:237], v[236:237], v[142:143]
	v_pk_add_f32 v[238:239], v[238:239], v[142:143]
	v_rcp_f32_e32 v232, v232
	v_rcp_f32_e32 v233, v233
	v_rcp_f32_e32 v234, v234
	v_rcp_f32_e32 v235, v235
	v_rcp_f32_e32 v236, v236
	v_rcp_f32_e32 v237, v237
	v_rcp_f32_e32 v238, v238
	v_rcp_f32_e32 v239, v239
	v_pk_mul_f32 v[80:81], v[80:81], v[232:233]
	v_pk_mul_f32 v[82:83], v[82:83], v[234:235]
	v_pk_mul_f32 v[72:73], v[72:73], v[236:237]
	v_pk_mul_f32 v[74:75], v[74:75], v[238:239]
	v_pk_mul_f32 v[80:81], v[76:77], v[80:81]
	v_pk_mul_f32 v[82:83], v[78:79], v[82:83]
	v_pk_mul_f32 v[72:73], v[68:69], v[72:73]
	v_pk_mul_f32 v[74:75], v[70:71], v[74:75]
	v_cvt_pk_bf16_f32 v248, v80, v81
	v_cvt_pk_bf16_f32 v249, v82, v83
	v_cvt_pk_bf16_f32 v250, v72, v73
	v_cvt_pk_bf16_f32 v251, v74, v75
	v_or_b32_e32 v232, 48, v141
	v_mad_i64_i32 v[252:253], s[8:9], v232, s20, v[246:247]
	v_lshl_add_u64 v[252:253], v[252:253], 0, s[46:47]
	v_lshl_add_u64 v[252:253], v[252:253], 0, v[2:3]
	v_permlane16_swap_b32_e32 v248, v250
	v_permlane16_swap_b32_e32 v249, v251
	global_store_dwordx4 v[252:253], v[248:251], off
	v_pk_mul_f32 v[232:233], v[64:65], v[0:1]
	v_pk_mul_f32 v[234:235], v[66:67], v[0:1]
	v_pk_mul_f32 v[236:237], v[56:57], v[0:1]
	v_pk_mul_f32 v[238:239], v[58:59], v[0:1]
	v_exp_f32_e32 v232, v232
	v_exp_f32_e32 v233, v233
	v_exp_f32_e32 v234, v234
	v_exp_f32_e32 v235, v235
	v_exp_f32_e32 v236, v236
	v_exp_f32_e32 v237, v237
	v_exp_f32_e32 v238, v238
	v_exp_f32_e32 v239, v239
	v_pk_add_f32 v[232:233], v[232:233], v[142:143]
	v_pk_add_f32 v[234:235], v[234:235], v[142:143]
	v_pk_add_f32 v[236:237], v[236:237], v[142:143]
	v_pk_add_f32 v[238:239], v[238:239], v[142:143]
	v_rcp_f32_e32 v232, v232
	v_rcp_f32_e32 v233, v233
	v_rcp_f32_e32 v234, v234
	v_rcp_f32_e32 v235, v235
	v_rcp_f32_e32 v236, v236
	v_rcp_f32_e32 v237, v237
	v_rcp_f32_e32 v238, v238
	v_rcp_f32_e32 v239, v239
	v_pk_mul_f32 v[64:65], v[64:65], v[232:233]
	v_pk_mul_f32 v[66:67], v[66:67], v[234:235]
	v_pk_mul_f32 v[56:57], v[56:57], v[236:237]
	v_pk_mul_f32 v[58:59], v[58:59], v[238:239]
	v_pk_mul_f32 v[64:65], v[60:61], v[64:65]
	v_pk_mul_f32 v[66:67], v[62:63], v[66:67]
	v_pk_mul_f32 v[56:57], v[52:53], v[56:57]
	v_pk_mul_f32 v[58:59], v[54:55], v[58:59]
	v_cvt_pk_bf16_f32 v240, v64, v65
	v_cvt_pk_bf16_f32 v241, v66, v67
	v_cvt_pk_bf16_f32 v242, v56, v57
	v_cvt_pk_bf16_f32 v243, v58, v59
	v_add_u32_e32 v232, 0x80, v141
	v_mad_i64_i32 v[244:245], s[8:9], v232, s20, v[246:247]
	v_lshl_add_u64 v[244:245], v[244:245], 0, s[46:47]
	v_lshl_add_u64 v[244:245], v[244:245], 0, v[2:3]
	v_permlane16_swap_b32_e32 v240, v242
	v_permlane16_swap_b32_e32 v241, v243
	global_store_dwordx4 v[244:245], v[240:243], off
	v_pk_mul_f32 v[232:233], v[48:49], v[0:1]
	v_pk_mul_f32 v[234:235], v[50:51], v[0:1]
	v_pk_mul_f32 v[236:237], v[40:41], v[0:1]
	v_pk_mul_f32 v[238:239], v[42:43], v[0:1]
	v_exp_f32_e32 v232, v232
	v_exp_f32_e32 v233, v233
	v_exp_f32_e32 v234, v234
	v_exp_f32_e32 v235, v235
	v_exp_f32_e32 v236, v236
	v_exp_f32_e32 v237, v237
	v_exp_f32_e32 v238, v238
	v_exp_f32_e32 v239, v239
	v_pk_add_f32 v[232:233], v[232:233], v[142:143]
	v_pk_add_f32 v[234:235], v[234:235], v[142:143]
	v_pk_add_f32 v[236:237], v[236:237], v[142:143]
	v_pk_add_f32 v[238:239], v[238:239], v[142:143]
	v_rcp_f32_e32 v232, v232
	v_rcp_f32_e32 v233, v233
	v_rcp_f32_e32 v234, v234
	v_rcp_f32_e32 v235, v235
	v_rcp_f32_e32 v236, v236
	v_rcp_f32_e32 v237, v237
	v_rcp_f32_e32 v238, v238
	v_rcp_f32_e32 v239, v239
	v_pk_mul_f32 v[48:49], v[48:49], v[232:233]
	v_pk_mul_f32 v[50:51], v[50:51], v[234:235]
	v_pk_mul_f32 v[40:41], v[40:41], v[236:237]
	v_pk_mul_f32 v[42:43], v[42:43], v[238:239]
	v_pk_mul_f32 v[48:49], v[44:45], v[48:49]
	v_pk_mul_f32 v[50:51], v[46:47], v[50:51]
	v_pk_mul_f32 v[40:41], v[36:37], v[40:41]
	v_pk_mul_f32 v[42:43], v[38:39], v[42:43]
	v_cvt_pk_bf16_f32 v248, v48, v49
	v_cvt_pk_bf16_f32 v249, v50, v51
	v_cvt_pk_bf16_f32 v250, v40, v41
	v_cvt_pk_bf16_f32 v251, v42, v43
	v_add_u32_e32 v232, 0x90, v141
	v_mad_i64_i32 v[252:253], s[8:9], v232, s20, v[246:247]
	v_lshl_add_u64 v[252:253], v[252:253], 0, s[46:47]
	v_lshl_add_u64 v[252:253], v[252:253], 0, v[2:3]
	v_permlane16_swap_b32_e32 v248, v250
	v_permlane16_swap_b32_e32 v249, v251
	global_store_dwordx4 v[252:253], v[248:251], off
	v_pk_mul_f32 v[232:233], v[32:33], v[0:1]
	v_pk_mul_f32 v[234:235], v[34:35], v[0:1]
	v_pk_mul_f32 v[236:237], v[24:25], v[0:1]
	v_pk_mul_f32 v[238:239], v[26:27], v[0:1]
	v_exp_f32_e32 v232, v232
	v_exp_f32_e32 v233, v233
	v_exp_f32_e32 v234, v234
	v_exp_f32_e32 v235, v235
	v_exp_f32_e32 v236, v236
	v_exp_f32_e32 v237, v237
	v_exp_f32_e32 v238, v238
	v_exp_f32_e32 v239, v239
	v_pk_add_f32 v[232:233], v[232:233], v[142:143]
	v_pk_add_f32 v[234:235], v[234:235], v[142:143]
	v_pk_add_f32 v[236:237], v[236:237], v[142:143]
	v_pk_add_f32 v[238:239], v[238:239], v[142:143]
	v_rcp_f32_e32 v232, v232
	v_rcp_f32_e32 v233, v233
	v_rcp_f32_e32 v234, v234
	v_rcp_f32_e32 v235, v235
	v_rcp_f32_e32 v236, v236
	v_rcp_f32_e32 v237, v237
	v_rcp_f32_e32 v238, v238
	v_rcp_f32_e32 v239, v239
	v_pk_mul_f32 v[32:33], v[32:33], v[232:233]
	v_pk_mul_f32 v[34:35], v[34:35], v[234:235]
	v_pk_mul_f32 v[24:25], v[24:25], v[236:237]
	v_pk_mul_f32 v[26:27], v[26:27], v[238:239]
	v_pk_mul_f32 v[32:33], v[28:29], v[32:33]
	v_pk_mul_f32 v[34:35], v[30:31], v[34:35]
	v_pk_mul_f32 v[24:25], v[20:21], v[24:25]
	v_pk_mul_f32 v[26:27], v[22:23], v[26:27]
	v_cvt_pk_bf16_f32 v240, v32, v33
	v_cvt_pk_bf16_f32 v241, v34, v35
	v_cvt_pk_bf16_f32 v242, v24, v25
	v_cvt_pk_bf16_f32 v243, v26, v27
	v_add_u32_e32 v232, 0xa0, v141
	v_mad_i64_i32 v[244:245], s[8:9], v232, s20, v[246:247]
	v_lshl_add_u64 v[244:245], v[244:245], 0, s[46:47]
	v_lshl_add_u64 v[244:245], v[244:245], 0, v[2:3]
	v_permlane16_swap_b32_e32 v240, v242
	v_permlane16_swap_b32_e32 v241, v243
	global_store_dwordx4 v[244:245], v[240:243], off
	v_pk_mul_f32 v[232:233], v[16:17], v[0:1]
	v_pk_mul_f32 v[234:235], v[18:19], v[0:1]
	v_pk_mul_f32 v[236:237], v[8:9], v[0:1]
	v_pk_mul_f32 v[238:239], v[10:11], v[0:1]
	v_exp_f32_e32 v232, v232
	v_exp_f32_e32 v233, v233
	v_exp_f32_e32 v234, v234
	v_exp_f32_e32 v235, v235
	v_exp_f32_e32 v236, v236
	v_exp_f32_e32 v237, v237
	v_exp_f32_e32 v238, v238
	v_exp_f32_e32 v239, v239
	v_pk_add_f32 v[232:233], v[232:233], v[142:143]
	v_pk_add_f32 v[234:235], v[234:235], v[142:143]
	v_pk_add_f32 v[236:237], v[236:237], v[142:143]
	v_pk_add_f32 v[238:239], v[238:239], v[142:143]
	v_rcp_f32_e32 v232, v232
	v_rcp_f32_e32 v233, v233
	v_rcp_f32_e32 v234, v234
	v_rcp_f32_e32 v235, v235
	v_rcp_f32_e32 v236, v236
	v_rcp_f32_e32 v237, v237
	v_rcp_f32_e32 v238, v238
	v_rcp_f32_e32 v239, v239
	v_pk_mul_f32 v[16:17], v[16:17], v[232:233]
	v_pk_mul_f32 v[18:19], v[18:19], v[234:235]
	v_pk_mul_f32 v[8:9], v[8:9], v[236:237]
	v_pk_mul_f32 v[10:11], v[10:11], v[238:239]
	v_pk_mul_f32 v[16:17], v[12:13], v[16:17]
	v_pk_mul_f32 v[18:19], v[14:15], v[18:19]
	v_pk_mul_f32 v[8:9], v[4:5], v[8:9]
	v_pk_mul_f32 v[10:11], v[6:7], v[10:11]
	v_cvt_pk_bf16_f32 v248, v16, v17
	v_cvt_pk_bf16_f32 v249, v18, v19
	v_cvt_pk_bf16_f32 v250, v8, v9
	v_cvt_pk_bf16_f32 v251, v10, v11
	v_add_u32_e32 v232, 0xb0, v141
	v_mad_i64_i32 v[252:253], s[8:9], v232, s20, v[246:247]
	v_lshl_add_u64 v[252:253], v[252:253], 0, s[46:47]
	v_lshl_add_u64 v[252:253], v[252:253], 0, v[2:3]
	v_permlane16_swap_b32_e32 v248, v250
	v_permlane16_swap_b32_e32 v249, v251
	global_store_dwordx4 v[252:253], v[248:251], off
	s_mov_b64 s[46:47], -1
	s_cbranch_vccnz .LBB0_162
	s_andn2_b64 vcc, exec, s[4:5]
	s_cbranch_vccnz .LBB0_161
	s_barrier
	s_branch .LBB0_161
